# hgrn readout loop: the four gate-column loads of an unrolled body issued at its top with counted waits (was load+vmcnt(0) per token, also waiting on the previous store)
# baseline (speedup 1.0000x reference)
; __device__ __forceinline__ float bf2f(unsigned v) { return __uint_as_float(v << 16); }
; __device__ __forceinline__ unsigned f2bf(float f) { return pk2(f, 0.f) & 0xffffu; }
; __device__ __forceinline__ float siluf_(float x) { return x * __builtin_amdgcn_rcpf(1.0f + __builtin_amdgcn_exp2f(-1.4426950408889634f * x)); }
; __device__ __forceinline__ void hgrn_out_phase(const Ctx& F, const Args& a, int l) {
;     ...
; #pragma unroll 4
;             for (int k = 0; k < 32; ++k) {
;                 const int tt = 32 * dir + k;
;                 const float ot = ob_f[tt * 64 + lane] + ob_b[tt * 64 + lane];
;                 const float ss = wave_sum(ot * ot);
;                 const float gg = bf2f(PB[(size_t)(rb + tt) * INW + C_BG + head * 64 + lane]);
;                 const float y = ot * (1.0f / sqrtf(ss * (1.f / 64.f) + EPSN)) * og * siluf_(gg);
;                 Y[(size_t)(rb + tt) * D + 256 + head * 64 + lane] = (bf16_t)f2bf(y);
;             }
.LBB0_314:
	s_add_i32 s101, s44, -3
	v_mad_i64_i32 v[248:249], s[4:5], s101, v205, v[116:117]
	global_load_ushort v238, v[248:249], off offset:3072
	s_add_i32 s101, s44, -2
	v_mad_i64_i32 v[248:249], s[4:5], s101, v205, v[116:117]
	global_load_ushort v239, v[248:249], off offset:3072
	s_add_i32 s101, s44, -1
	v_mad_i64_i32 v[248:249], s[4:5], s101, v205, v[116:117]
	global_load_ushort v240, v[248:249], off offset:3072
	v_mad_i64_i32 v[248:249], s[4:5], s44, v205, v[116:117]
	global_load_ushort v241, v[248:249], off offset:3072
	v_add_u32_e32 v4, s6, v0
	v_add_u32_e32 v5, 0x14000, v4
	ds_read2st64_b32 v[2:3], v4 offset0:32 offset1:33
	ds_read_b32 v5, v5
	s_add_i32 s22, s44, -3
	s_ashr_i32 s23, s22, 31
	s_add_i32 s82, s44, -1
	s_ashr_i32 s83, s82, 31
	s_waitcnt lgkmcnt(0)
	v_add_f32_e32 v2, v2, v5
	v_mul_f32_e32 v5, v2, v2
	s_nop 1
	v_mov_b32_dpp v5, v5 quad_perm:[1,0,3,2] row_mask:0xf bank_mask:0xf
	s_ashr_i32 s45, s44, 31
	s_addk_i32 s6, 0x400
	s_waitcnt lgkmcnt(0)
	v_fmac_f32_e32 v5, v2, v2
	s_nop 1
	v_mov_b32_dpp v6, v5 quad_perm:[2,3,0,1] row_mask:0xf bank_mask:0xf
	s_waitcnt lgkmcnt(0)
	v_add_f32_e32 v5, v5, v6
	s_nop 1
	v_mov_b32_dpp v6, v5 row_half_mirror row_mask:0xf bank_mask:0xf
	s_waitcnt lgkmcnt(0)
	v_add_f32_e32 v5, v5, v6
	s_nop 1
	v_mov_b32_dpp v6, v5 row_ror:8 row_mask:0xf bank_mask:0xf
	s_waitcnt lgkmcnt(0)
	v_add_f32_e32 v5, v5, v6
	v_mov_b32_e32 v6, v5
	s_nop 1
	v_permlane16_swap_b32_e32 v5, v6
	s_waitcnt lgkmcnt(0)
	v_add_f32_e32 v5, v5, v6
	v_mov_b32_e32 v6, v5
	s_nop 1
	v_permlane32_swap_b32_e32 v5, v6
	v_add_f32_e32 v5, v5, v6
	v_mad_i64_i32 v[6:7], s[4:5], s22, v205, v[116:117]
	s_nop 0
	v_fmamk_f32 v5, v5, 0x3c800000, v193
	v_cmp_gt_f32_e32 vcc, s41, v5
	s_waitcnt vmcnt(3)
	v_lshlrev_b32_e32 v7, 16, v238
	v_mul_f32_e32 v6, 0x4f800000, v5
	v_cndmask_b32_e32 v5, v5, v6, vcc
	v_sqrt_f32_e32 v6, v5
	s_nop 0
	v_add_u32_e32 v8, -1, v6
	v_fma_f32 v9, -v8, v6, v5
	v_cmp_ge_f32_e64 s[4:5], 0, v9
	v_add_u32_e32 v9, 1, v6
	s_nop 0
	v_cndmask_b32_e64 v8, v6, v8, s[4:5]
	v_fma_f32 v6, -v9, v6, v5
	v_cmp_lt_f32_e64 s[4:5], 0, v6
	s_nop 1
	v_cndmask_b32_e64 v6, v8, v9, s[4:5]
	v_mul_f32_e32 v8, 0x37800000, v6
	v_cndmask_b32_e32 v6, v6, v8, vcc
	v_cmp_class_f32_e32 vcc, v5, v202
	s_nop 1
	v_cndmask_b32_e32 v5, v6, v5, vcc
	v_div_scale_f32 v6, s[4:5], v5, v5, 1.0
	v_rcp_f32_e32 v8, v6
	s_lshl_b64 s[4:5], s[22:23], 11
	s_add_i32 s22, s44, -2
	s_ashr_i32 s23, s22, 31
	v_fma_f32 v9, -v6, v8, 1.0
	v_fmac_f32_e32 v8, v9, v8
	v_div_scale_f32 v9, vcc, 1.0, v5, 1.0
	v_mul_f32_e32 v10, v9, v8
	v_fma_f32 v11, -v6, v10, v9
	v_fmac_f32_e32 v10, v11, v8
	v_fma_f32 v6, -v6, v10, v9
	v_div_fmas_f32 v6, v6, v8, v10
	v_div_fixup_f32 v5, v6, v5, 1.0
	v_mul_f32_e32 v6, v2, v5
	v_mul_f32_e32 v2, 0xbfb8aa3b, v7
	v_exp_f32_e32 v2, v2
	s_nop 0
	v_add_f32_e32 v2, 1.0, v2
	v_rcp_f32_e32 v99, v2
	s_nop 0
	v_pk_mul_f32 v[6:7], v[98:99], v[6:7]
	s_nop 0
	v_mul_f32_e32 v2, v6, v7
	v_cvt_pk_bf16_f32 v2, v2, s0
	v_lshl_add_u64 v[6:7], v[112:113], 0, s[4:5]
	global_store_short v[6:7], v2, off
	v_add_u32_e32 v2, 0x14100, v4
	ds_read_b32 v2, v2
	s_waitcnt lgkmcnt(0)
	v_add_f32_e32 v5, v3, v2
	v_mul_f32_e32 v2, v5, v5
	s_nop 1
	v_mov_b32_dpp v2, v2 quad_perm:[1,0,3,2] row_mask:0xf bank_mask:0xf
	s_waitcnt lgkmcnt(0)
	v_fmac_f32_e32 v2, v5, v5
	s_nop 1
	v_mov_b32_dpp v3, v2 quad_perm:[2,3,0,1] row_mask:0xf bank_mask:0xf
	s_waitcnt lgkmcnt(0)
	v_add_f32_e32 v2, v2, v3
	s_nop 1
	v_mov_b32_dpp v3, v2 row_half_mirror row_mask:0xf bank_mask:0xf
	s_waitcnt lgkmcnt(0)
	v_add_f32_e32 v2, v2, v3
	s_nop 1
	v_mov_b32_dpp v3, v2 row_ror:8 row_mask:0xf bank_mask:0xf
	s_waitcnt lgkmcnt(0)
	v_add_f32_e32 v2, v2, v3
	v_mov_b32_e32 v3, v2
	s_nop 1
	v_permlane16_swap_b32_e32 v2, v3
	s_waitcnt lgkmcnt(0)
	v_add_f32_e32 v2, v2, v3
	v_mov_b32_e32 v3, v2
	s_nop 1
	v_permlane32_swap_b32_e32 v2, v3
	v_add_f32_e32 v6, v2, v3
	v_mad_i64_i32 v[2:3], s[4:5], s22, v205, v[116:117]
	s_nop 0
	s_waitcnt vmcnt(3)
	v_lshlrev_b32_e32 v3, 16, v239
	v_fmamk_f32 v2, v6, 0x3c800000, v193
	v_cmp_gt_f32_e32 vcc, s41, v2
	v_mul_f32_e32 v6, 0x4f800000, v2
	s_nop 0
	v_cndmask_b32_e32 v2, v2, v6, vcc
	v_sqrt_f32_e32 v6, v2
	s_nop 0
	v_add_u32_e32 v7, -1, v6
	v_fma_f32 v8, -v7, v6, v2
	v_cmp_ge_f32_e64 s[4:5], 0, v8
	v_add_u32_e32 v8, 1, v6
	s_nop 0
	v_cndmask_b32_e64 v7, v6, v7, s[4:5]
	v_fma_f32 v6, -v8, v6, v2
	v_cmp_lt_f32_e64 s[4:5], 0, v6
	s_nop 1
	v_cndmask_b32_e64 v6, v7, v8, s[4:5]
	v_mul_f32_e32 v7, 0x37800000, v6
	v_cndmask_b32_e32 v6, v6, v7, vcc
	v_cmp_class_f32_e32 vcc, v2, v202
	s_nop 1
	v_cndmask_b32_e32 v2, v6, v2, vcc
	v_div_scale_f32 v6, s[4:5], v2, v2, 1.0
	v_rcp_f32_e32 v7, v6
	s_lshl_b64 s[4:5], s[22:23], 11
	v_fma_f32 v8, -v6, v7, 1.0
	v_fmac_f32_e32 v7, v8, v7
	v_div_scale_f32 v8, vcc, 1.0, v2, 1.0
	v_mul_f32_e32 v9, v8, v7
	v_fma_f32 v10, -v6, v9, v8
	v_fmac_f32_e32 v9, v10, v7
	v_fma_f32 v6, -v6, v9, v8
	v_div_fmas_f32 v6, v6, v7, v9
	v_div_fixup_f32 v2, v6, v2, 1.0
	v_mul_f32_e32 v2, v5, v2
	v_mul_f32_e32 v5, 0xbfb8aa3b, v3
	v_exp_f32_e32 v5, v5
	s_nop 0
	v_add_f32_e32 v5, 1.0, v5
	v_rcp_f32_e32 v99, v5
	s_nop 0
	v_pk_mul_f32 v[2:3], v[98:99], v[2:3]
	s_nop 0
	v_mul_f32_e32 v2, v2, v3
	v_cvt_pk_bf16_f32 v5, v2, s0
	v_lshl_add_u64 v[2:3], v[112:113], 0, s[4:5]
	global_store_short v[2:3], v5, off
	v_add_u32_e32 v5, 0x14200, v4
	ds_read2st64_b32 v[2:3], v4 offset0:34 offset1:35
	ds_read_b32 v5, v5
	s_waitcnt lgkmcnt(0)
; __device__ __forceinline__ float bf2f(unsigned v) { return __uint_as_float(v << 16); }
; __device__ __forceinline__ unsigned f2bf(float f) { return pk2(f, 0.f) & 0xffffu; }
; __device__ __forceinline__ float siluf_(float x) { return x * __builtin_amdgcn_rcpf(1.0f + __builtin_amdgcn_exp2f(-1.4426950408889634f * x)); }
; __device__ __forceinline__ void hgrn_out_phase(const Ctx& F, const Args& a, int l) {
;     ...
; #pragma unroll 4
;             for (int k = 0; k < 32; ++k) {
;                 const int tt = 32 * dir + k;
;                 const float ot = ob_f[tt * 64 + lane] + ob_b[tt * 64 + lane];
;                 const float ss = wave_sum(ot * ot);
;                 const float gg = bf2f(PB[(size_t)(rb + tt) * INW + C_BG + head * 64 + lane]);
;                 const float y = ot * (1.0f / sqrtf(ss * (1.f / 64.f) + EPSN)) * og * siluf_(gg);
;                 Y[(size_t)(rb + tt) * D + 256 + head * 64 + lane] = (bf16_t)f2bf(y);
;             }
;         }
;         __syncthreads();
;     }
	v_add_f32_e32 v2, v2, v5
	v_mul_f32_e32 v5, v2, v2
	s_nop 1
	v_mov_b32_dpp v5, v5 quad_perm:[1,0,3,2] row_mask:0xf bank_mask:0xf
	s_waitcnt lgkmcnt(0)
	v_fmac_f32_e32 v5, v2, v2
	s_nop 1
	v_mov_b32_dpp v6, v5 quad_perm:[2,3,0,1] row_mask:0xf bank_mask:0xf
	s_waitcnt lgkmcnt(0)
	v_add_f32_e32 v5, v5, v6
	s_nop 1
	v_mov_b32_dpp v6, v5 row_half_mirror row_mask:0xf bank_mask:0xf
	s_waitcnt lgkmcnt(0)
	v_add_f32_e32 v5, v5, v6
	s_nop 1
	v_mov_b32_dpp v6, v5 row_ror:8 row_mask:0xf bank_mask:0xf
	s_waitcnt lgkmcnt(0)
	v_add_f32_e32 v5, v5, v6
	v_mov_b32_e32 v6, v5
	s_nop 1
	v_permlane16_swap_b32_e32 v5, v6
	s_waitcnt lgkmcnt(0)
	v_add_f32_e32 v5, v5, v6
	v_mov_b32_e32 v6, v5
	s_nop 1
	v_permlane32_swap_b32_e32 v5, v6
	v_add_f32_e32 v5, v5, v6
	v_mad_i64_i32 v[6:7], s[4:5], s82, v205, v[116:117]
	s_nop 0
	v_fmamk_f32 v5, v5, 0x3c800000, v193
	v_cmp_gt_f32_e32 vcc, s41, v5
	s_waitcnt vmcnt(3)
	v_lshlrev_b32_e32 v7, 16, v240
	v_mul_f32_e32 v6, 0x4f800000, v5
	v_cndmask_b32_e32 v5, v5, v6, vcc
	v_sqrt_f32_e32 v6, v5
	s_nop 0
	v_add_u32_e32 v8, -1, v6
	v_fma_f32 v9, -v8, v6, v5
	v_cmp_ge_f32_e64 s[4:5], 0, v9
	v_add_u32_e32 v9, 1, v6
	s_nop 0
	v_cndmask_b32_e64 v8, v6, v8, s[4:5]
	v_fma_f32 v6, -v9, v6, v5
	v_cmp_lt_f32_e64 s[4:5], 0, v6
	s_nop 1
	v_cndmask_b32_e64 v6, v8, v9, s[4:5]
	v_mul_f32_e32 v8, 0x37800000, v6
	v_cndmask_b32_e32 v6, v6, v8, vcc
	v_cmp_class_f32_e32 vcc, v5, v202
	s_nop 1
	v_cndmask_b32_e32 v5, v6, v5, vcc
	v_div_scale_f32 v6, s[4:5], v5, v5, 1.0
	v_rcp_f32_e32 v8, v6
	s_lshl_b64 s[4:5], s[82:83], 11
	v_fma_f32 v9, -v6, v8, 1.0
	v_fmac_f32_e32 v8, v9, v8
	v_div_scale_f32 v9, vcc, 1.0, v5, 1.0
	v_mul_f32_e32 v10, v9, v8
	v_fma_f32 v11, -v6, v10, v9
	v_fmac_f32_e32 v10, v11, v8
	v_fma_f32 v6, -v6, v10, v9
	v_div_fmas_f32 v6, v6, v8, v10
	v_div_fixup_f32 v5, v6, v5, 1.0
	v_mul_f32_e32 v6, v2, v5
	v_mul_f32_e32 v2, 0xbfb8aa3b, v7
	v_exp_f32_e32 v2, v2
	s_nop 0
	v_add_f32_e32 v2, 1.0, v2
	v_rcp_f32_e32 v99, v2
	s_nop 0
	v_pk_mul_f32 v[6:7], v[98:99], v[6:7]
	s_nop 0
	v_mul_f32_e32 v2, v6, v7
	v_cvt_pk_bf16_f32 v2, v2, s0
	v_lshl_add_u64 v[6:7], v[112:113], 0, s[4:5]
	global_store_short v[6:7], v2, off
	v_add_u32_e32 v2, 0x14300, v4
	ds_read_b32 v2, v2
	s_waitcnt lgkmcnt(0)
	v_add_f32_e32 v2, v3, v2
	v_mul_f32_e32 v3, v2, v2
	s_nop 1
	v_mov_b32_dpp v3, v3 quad_perm:[1,0,3,2] row_mask:0xf bank_mask:0xf
	s_waitcnt lgkmcnt(0)
	v_fmac_f32_e32 v3, v2, v2
	s_nop 1
	v_mov_b32_dpp v4, v3 quad_perm:[2,3,0,1] row_mask:0xf bank_mask:0xf
	s_waitcnt lgkmcnt(0)
	v_add_f32_e32 v3, v3, v4
	s_nop 1
	v_mov_b32_dpp v4, v3 row_half_mirror row_mask:0xf bank_mask:0xf
	s_waitcnt lgkmcnt(0)
	v_add_f32_e32 v3, v3, v4
	s_nop 1
	v_mov_b32_dpp v4, v3 row_ror:8 row_mask:0xf bank_mask:0xf
	s_waitcnt lgkmcnt(0)
	v_add_f32_e32 v3, v3, v4
	v_mov_b32_e32 v4, v3
	s_nop 1
	v_permlane16_swap_b32_e32 v3, v4
	s_waitcnt lgkmcnt(0)
	v_add_f32_e32 v3, v3, v4
	v_mov_b32_e32 v4, v3
	s_nop 1
	v_permlane32_swap_b32_e32 v3, v4
	v_add_f32_e32 v6, v3, v4
	v_mad_i64_i32 v[4:5], s[4:5], s44, v205, v[116:117]
	s_nop 0
	v_fmamk_f32 v4, v6, 0x3c800000, v193
	v_cmp_gt_f32_e32 vcc, s41, v4
	v_mul_f32_e32 v5, 0x4f800000, v4
	s_waitcnt vmcnt(3)
	v_lshlrev_b32_e32 v3, 16, v241
	v_cndmask_b32_e32 v4, v4, v5, vcc
	v_sqrt_f32_e32 v5, v4
	s_nop 0
	v_add_u32_e32 v6, -1, v5
	v_fma_f32 v7, -v6, v5, v4
	v_cmp_ge_f32_e64 s[4:5], 0, v7
	v_add_u32_e32 v7, 1, v5
	s_nop 0
	v_cndmask_b32_e64 v6, v5, v6, s[4:5]
	v_fma_f32 v5, -v7, v5, v4
	v_cmp_lt_f32_e64 s[4:5], 0, v5
	s_nop 1
	v_cndmask_b32_e64 v5, v6, v7, s[4:5]
	v_mul_f32_e32 v6, 0x37800000, v5
	v_cndmask_b32_e32 v5, v5, v6, vcc
	v_cmp_class_f32_e32 vcc, v4, v202
	s_nop 1
	v_cndmask_b32_e32 v4, v5, v4, vcc
	v_div_scale_f32 v5, s[4:5], v4, v4, 1.0
	v_rcp_f32_e32 v6, v5
	s_lshl_b64 s[4:5], s[44:45], 11
	s_add_i32 s44, s44, 4
	s_cmp_eq_u32 s6, 0
	v_fma_f32 v7, -v5, v6, 1.0
	v_fmac_f32_e32 v6, v7, v6
	v_div_scale_f32 v7, vcc, 1.0, v4, 1.0
	v_mul_f32_e32 v8, v7, v6
	v_fma_f32 v9, -v5, v8, v7
	v_fmac_f32_e32 v8, v9, v6
	v_fma_f32 v5, -v5, v8, v7
	v_div_fmas_f32 v5, v5, v6, v8
	v_div_fixup_f32 v4, v5, v4, 1.0
	v_mul_f32_e32 v2, v2, v4
	v_mul_f32_e32 v4, 0xbfb8aa3b, v3
	v_exp_f32_e32 v4, v4
	s_nop 0
	v_add_f32_e32 v4, 1.0, v4
	v_rcp_f32_e32 v99, v4
	s_nop 0
	v_pk_mul_f32 v[2:3], v[98:99], v[2:3]
	s_nop 0
	v_mul_f32_e32 v2, v2, v3
	v_cvt_pk_bf16_f32 v4, v2, s0
	v_lshl_add_u64 v[2:3], v[112:113], 0, s[4:5]
	global_store_short v[2:3], v4, off
	s_cbranch_scc0 .LBB0_314
	s_addk_i32 s84, 0x270
	s_nop 0
	s_addk_i32 s85, 0x2700
	s_nop 0
	v_readlane_b32 s66, v253, 19
	v_readlane_b32 s46, v253, 24
	v_readlane_b32 s52, v253, 26
	s_sub_i32 s2, s84, 0x400
	s_cmp_gt_u32 s2, 15
	s_mov_b32 s93, 0xff61b1e6
	s_mov_b32 s94, 0xc2ce8ed0
	s_mov_b32 s95, 0x42b17218
	s_mov_b32 s36, 0x3fb8aa3b
	v_readlane_b32 s67, v253, 20
	v_readlane_b32 s47, v253, 25
	v_readlane_b32 s53, v253, 27
	s_barrier
	s_cbranch_scc0 .LBB0_313
